# FoX unmasked tile: the 64 v_sub_f32 that initialise S^T (ctq - c) replaced by four rank-2 v_mfma_f32_32x32x2_f32 (f32 operands, bitwise identical), moving that work from the VALU to the idle matrix pi
# baseline (speedup 1.0000x reference)
.LBB0_391:
	s_and_b64 vcc, exec, s[10:11]
	s_cbranch_vccz .LBB0_393
	v_and_b32_e32 v112, 31, v198
	s_mov_b32 vcc_lo, 0
	v_lshl_add_u32 v112, v112, 2, s54
	s_mov_b32 vcc_hi, -1
	ds_read_b32 v113, v112
	ds_read_b32 v114, v112 offset:128
	v_add3_u32 v234, s86, v229, v227
	v_cndmask_b32_e64 v115, v48, 1.0, vcc
	ds_read_b128 v[2:5], v234 offset:96
	ds_read_b128 v[6:9], v234 offset:64
	ds_read_b128 v[10:13], v234
	ds_read_b128 v[120:123], v234 offset:32
	ds_read_b128 v[124:127], v234 offset:4704
	ds_read_b128 v[128:131], v234 offset:4672
	ds_read_b128 v[132:135], v234 offset:4640
	ds_read_b128 v[136:139], v234 offset:4608
	s_waitcnt lgkmcnt(8)
	v_xor_b32_e32 v113, 0x80000000, v113
	v_xor_b32_e32 v114, 0x80000000, v114
	v_cndmask_b32_e64 v113, 1.0, v113, vcc
	v_cndmask_b32_e64 v114, 1.0, v114, vcc
	s_nop 1
	v_mfma_f32_32x32x2_f32 v[96:111], v113, v115, 0
	v_mfma_f32_32x32x2_f32 v[32:47], v114, v115, 0
	s_waitcnt lgkmcnt(4)
	v_mfma_f32_32x32x16_bf16 v[96:111], v[10:13], v[144:147], v[96:111]
	s_waitcnt lgkmcnt(0)
	v_mfma_f32_32x32x16_bf16 v[96:111], v[120:123], v[148:151], v[96:111]
	v_mfma_f32_32x32x16_bf16 v[32:47], v[136:139], v[144:147], v[32:47]
	v_mfma_f32_32x32x16_bf16 v[32:47], v[132:135], v[148:151], v[32:47]
	v_mfma_f32_32x32x16_bf16 v[96:111], v[6:9], v[152:155], v[96:111]
	v_mfma_f32_32x32x16_bf16 v[32:47], v[128:131], v[152:155], v[32:47]
	v_mfma_f32_32x32x16_bf16 v[96:111], v[2:5], v[156:159], v[96:111]
	v_add3_u32 v4, s77, v230, v211
	ds_read_b64_tr_b16 v[6:7], v4 offset:36864
	ds_read_b64_tr_b16 v[8:9], v4 offset:38400
	ds_read_b64_tr_b16 v[12:13], v4 offset:38464
	ds_read_b64_tr_b16 v[10:11], v4 offset:36928
	ds_read_b64_tr_b16 v[112:113], v4 offset:39936
	ds_read_b64_tr_b16 v[114:115], v4 offset:41472
	ds_read_b64_tr_b16 v[118:119], v4 offset:41536
	ds_read_b64_tr_b16 v[116:117], v4 offset:40000
	v_mfma_f32_32x32x16_bf16 v[32:47], v[124:127], v[156:159], v[32:47]
	s_nop 1
	v_exp_f32_e32 v2, v96
	v_exp_f32_e32 v15, v97
	v_exp_f32_e32 v121, v98
	v_exp_f32_e32 v123, v99
	v_exp_f32_e32 v125, v100
	v_exp_f32_e32 v127, v101
	v_exp_f32_e32 v129, v102
	v_exp_f32_e32 v131, v103
	v_exp_f32_e32 v133, v104
	v_exp_f32_e32 v135, v105
	v_exp_f32_e32 v137, v106
	v_exp_f32_e32 v139, v107
	v_exp_f32_e32 v141, v108
	v_exp_f32_e32 v109, v109
	v_exp_f32_e32 v143, v110
	v_exp_f32_e32 v111, v111
	v_cvt_pk_bf16_f32 v96, v2, v15
	v_cvt_pk_bf16_f32 v97, v121, v123
	v_cvt_pk_bf16_f32 v98, v125, v127
	v_cvt_pk_bf16_f32 v99, v129, v131
	v_cvt_pk_bf16_f32 v100, v133, v135
	v_cvt_pk_bf16_f32 v101, v137, v139
	v_cvt_pk_bf16_f32 v102, v141, v109
	v_cvt_pk_bf16_f32 v103, v143, v111
	s_waitcnt lgkmcnt(0)
	v_add_f32_e32 v3, 0, v2
	v_mfma_f32_32x32x16_bf16 v[64:79], v[6:9], v[96:99], v[64:79]
	v_mfma_f32_32x32x16_bf16 v[80:95], v[10:13], v[96:99], v[80:95]
	ds_read_b64_tr_b16 v[6:7], v4 offset:43008
	ds_read_b64_tr_b16 v[8:9], v4 offset:44544
	ds_read_b64_tr_b16 v[12:13], v4 offset:44608
	ds_read_b64_tr_b16 v[10:11], v4 offset:43072
	ds_read_b64_tr_b16 v[96:97], v4 offset:46080
	ds_read_b64_tr_b16 v[98:99], v4 offset:47616
	ds_read_b64_tr_b16 v[106:107], v4 offset:47680
	ds_read_b64_tr_b16 v[104:105], v4 offset:46144
	v_mfma_f32_32x32x16_bf16 v[64:79], v[112:115], v[100:103], v[64:79]
	v_mfma_f32_32x32x16_bf16 v[80:95], v[116:119], v[100:103], v[80:95]
	v_exp_f32_e32 v14, v32
	v_exp_f32_e32 v120, v33
	v_exp_f32_e32 v122, v34
	v_exp_f32_e32 v124, v35
	v_mov_b32_e32 v2, v1
	v_add_f32_e32 v2, v14, v2
	v_add_f32_e32 v3, v15, v3
	v_exp_f32_e32 v126, v36
	v_add_f32_e32 v2, v120, v2
	v_add_f32_e32 v3, v121, v3
	v_exp_f32_e32 v128, v37
	v_add_f32_e32 v2, v122, v2
	v_add_f32_e32 v3, v123, v3
	v_exp_f32_e32 v130, v38
	v_add_f32_e32 v2, v124, v2
	v_add_f32_e32 v3, v125, v3
	v_exp_f32_e32 v132, v39
	v_exp_f32_e32 v134, v40
	v_add_f32_e32 v2, v126, v2
	v_add_f32_e32 v3, v127, v3
	v_exp_f32_e32 v136, v41
	v_add_f32_e32 v2, v128, v2
	v_add_f32_e32 v3, v129, v3
	v_exp_f32_e32 v138, v42
	v_exp_f32_e32 v140, v43
	v_exp_f32_e32 v108, v44
	v_exp_f32_e32 v142, v45
	v_exp_f32_e32 v110, v46
	v_exp_f32_e32 v192, v47
	v_add_f32_e32 v2, v130, v2
	v_add_f32_e32 v3, v131, v3
	v_cvt_pk_bf16_f32 v32, v14, v120
	v_cvt_pk_bf16_f32 v33, v122, v124
	v_cvt_pk_bf16_f32 v34, v126, v128
	v_cvt_pk_bf16_f32 v35, v130, v132
	v_cvt_pk_bf16_f32 v36, v134, v136
	v_cvt_pk_bf16_f32 v37, v138, v140
	v_cvt_pk_bf16_f32 v38, v108, v142
	v_cvt_pk_bf16_f32 v39, v110, v192
	s_waitcnt lgkmcnt(0)
	v_add_f32_e32 v2, v132, v2
	v_add_f32_e32 v3, v133, v3
	v_mfma_f32_32x32x16_bf16 v[64:79], v[6:9], v[32:35], v[64:79]
	v_add_f32_e64 v2, v134, v2
	v_add_f32_e64 v3, v135, v3
	v_add_f32_e64 v2, v136, v2
	v_add_f32_e64 v3, v137, v3
	v_add_f32_e64 v2, v138, v2
	v_add_f32_e64 v3, v139, v3
	v_add_f32_e32 v2, v140, v2
	v_add_f32_e32 v3, v141, v3
	v_mfma_f32_32x32x16_bf16 v[80:95], v[10:13], v[32:35], v[80:95]
	v_add_f32_e64 v2, v108, v2
	v_add_f32_e64 v3, v109, v3
	v_add_f32_e64 v2, v142, v2
	v_add_f32_e64 v3, v143, v3
	v_add_f32_e64 v2, v110, v2
	v_add_f32_e64 v3, v111, v3
	v_add_f32_e32 v2, v192, v2
	v_add_f32_e32 v3, v193, v3
	v_mfma_f32_32x32x16_bf16 v[64:79], v[96:99], v[36:39], v[64:79]
	v_pk_add_f32 v[2:3], v[2:3], v[2:3] op_sel_hi:[0,1]
	v_mfma_f32_32x32x16_bf16 v[80:95], v[104:107], v[36:39], v[80:95]
	v_and_b32_e32 v6, 31, v198
	v_lshl_add_u32 v6, v6, 2, s54
	ds_read_b32 v8, v6 offset:384
	ds_read_b32 v7, v6 offset:256
	v_cndmask_b32_e64 v9, v48, 1.0, vcc
	ds_read_b128 v[112:115], v234 offset:9312
	ds_read_b128 v[116:119], v234 offset:9280
	ds_read_b128 v[120:123], v234 offset:9216
	ds_read_b128 v[124:127], v234 offset:9248
	ds_read_b128 v[128:131], v234 offset:13920
	ds_read_b128 v[132:135], v234 offset:13888
	ds_read_b128 v[136:139], v234 offset:13856
	ds_read_b128 v[140:143], v234 offset:13824
	s_waitcnt lgkmcnt(8)
	v_xor_b32_e32 v8, 0x80000000, v8
	v_xor_b32_e32 v7, 0x80000000, v7
	v_cndmask_b32_e64 v8, 1.0, v8, vcc
	v_cndmask_b32_e64 v7, 1.0, v7, vcc
	s_nop 1
	v_mfma_f32_32x32x2_f32 v[32:47], v8, v9, 0
	v_mfma_f32_32x32x2_f32 v[96:111], v7, v9, 0
	s_waitcnt lgkmcnt(0)
	s_nop 0
	v_mfma_f32_32x32x16_bf16 v[32:47], v[140:143], v[144:147], v[32:47]
	v_mfma_f32_32x32x16_bf16 v[96:111], v[120:123], v[144:147], v[96:111]
	v_mfma_f32_32x32x16_bf16 v[96:111], v[124:127], v[148:151], v[96:111]
	v_mfma_f32_32x32x16_bf16 v[32:47], v[136:139], v[148:151], v[32:47]
	v_mfma_f32_32x32x16_bf16 v[96:111], v[116:119], v[152:155], v[96:111]
	v_mfma_f32_32x32x16_bf16 v[32:47], v[132:135], v[152:155], v[32:47]
	v_mfma_f32_32x32x16_bf16 v[96:111], v[112:115], v[156:159], v[96:111]
	ds_read_b64_tr_b16 v[6:7], v4 offset:49152
	ds_read_b64_tr_b16 v[8:9], v4 offset:50688
	ds_read_b64_tr_b16 v[10:11], v4 offset:52224
	ds_read_b64_tr_b16 v[12:13], v4 offset:53760
	ds_read_b64_tr_b16 v[112:113], v4 offset:49216
	ds_read_b64_tr_b16 v[114:115], v4 offset:50752
	ds_read_b64_tr_b16 v[116:117], v4 offset:52288
	ds_read_b64_tr_b16 v[118:119], v4 offset:53824
	v_mfma_f32_32x32x16_bf16 v[32:47], v[128:131], v[156:159], v[32:47]
	s_nop 2
	v_exp_f32_e32 v0, v96
	v_exp_f32_e32 v5, v97
	v_exp_f32_e32 v15, v98
	v_exp_f32_e32 v121, v99
	v_exp_f32_e32 v123, v100
	v_exp_f32_e32 v125, v101
	v_exp_f32_e32 v127, v102
	v_exp_f32_e32 v129, v103
	v_exp_f32_e32 v131, v104
	v_exp_f32_e32 v133, v105
	v_exp_f32_e32 v135, v106
	v_exp_f32_e32 v137, v107
	v_exp_f32_e32 v139, v108
	v_exp_f32_e32 v109, v109
	v_exp_f32_e32 v141, v110
	v_exp_f32_e32 v111, v111
	v_cvt_pk_bf16_f32 v96, v0, v5
	v_cvt_pk_bf16_f32 v97, v15, v121
	v_cvt_pk_bf16_f32 v98, v123, v125
	v_cvt_pk_bf16_f32 v99, v127, v129
	v_cvt_pk_bf16_f32 v100, v131, v133
	v_cvt_pk_bf16_f32 v101, v135, v137
	v_cvt_pk_bf16_f32 v102, v139, v109
	v_cvt_pk_bf16_f32 v103, v141, v111
	s_waitcnt lgkmcnt(0)
	v_add_f32_e32 v143, 0, v0
	v_mfma_f32_32x32x16_bf16 v[64:79], v[6:9], v[96:99], v[64:79]
	v_mfma_f32_32x32x16_bf16 v[64:79], v[10:13], v[100:103], v[64:79]
	v_mfma_f32_32x32x16_bf16 v[80:95], v[112:115], v[96:99], v[80:95]
	ds_read_b64_tr_b16 v[6:7], v4 offset:55296
	ds_read_b64_tr_b16 v[8:9], v4 offset:56832
	ds_read_b64_tr_b16 v[12:13], v4 offset:56896
	ds_read_b64_tr_b16 v[10:11], v4 offset:55360
	ds_read_b64_tr_b16 v[96:97], v4 offset:58368
	ds_read_b64_tr_b16 v[98:99], v4 offset:59904
	ds_read_b64_tr_b16 v[106:107], v4 offset:59968
	ds_read_b64_tr_b16 v[104:105], v4 offset:58432
	v_mfma_f32_32x32x16_bf16 v[80:95], v[116:119], v[100:103], v[80:95]
	v_exp_f32_e32 v4, v32
	v_exp_f32_e32 v14, v33
	v_exp_f32_e32 v120, v34
	v_exp_f32_e32 v122, v35
	v_exp_f32_e32 v124, v36
	v_exp_f32_e32 v126, v37
	v_exp_f32_e32 v128, v38
	v_exp_f32_e32 v130, v39
	v_exp_f32_e32 v132, v40
	v_exp_f32_e32 v134, v41
	v_exp_f32_e32 v136, v42
	v_exp_f32_e32 v138, v43
	v_exp_f32_e32 v108, v44
	v_exp_f32_e32 v140, v45
	v_exp_f32_e32 v110, v46
	v_exp_f32_e32 v2, v47
	v_cvt_pk_bf16_f32 v32, v4, v14
	v_cvt_pk_bf16_f32 v33, v120, v122
	v_cvt_pk_bf16_f32 v34, v124, v126
	v_cvt_pk_bf16_f32 v35, v128, v130
	v_cvt_pk_bf16_f32 v36, v132, v134
	v_cvt_pk_bf16_f32 v37, v136, v138
	v_cvt_pk_bf16_f32 v38, v108, v140
	v_cvt_pk_bf16_f32 v39, v110, v2
	s_waitcnt lgkmcnt(0)
	v_mov_b32_e32 v142, v1
	v_mfma_f32_32x32x16_bf16 v[64:79], v[6:9], v[32:35], v[64:79]
	v_add_f32_e64 v4, v4, v142
	v_add_f32_e64 v5, v5, v143
	v_add_f32_e64 v4, v14, v4
	v_add_f32_e64 v5, v15, v5
	v_add_f32_e64 v4, v120, v4
	v_add_f32_e64 v5, v121, v5
	v_add_f32_e32 v4, v122, v4
	v_add_f32_e32 v5, v123, v5
	v_mfma_f32_32x32x16_bf16 v[80:95], v[10:13], v[32:35], v[80:95]
	v_add_f32_e64 v4, v124, v4
	v_add_f32_e64 v5, v125, v5
	v_add_f32_e64 v4, v126, v4
	v_add_f32_e64 v5, v127, v5
	v_add_f32_e64 v4, v128, v4
	v_add_f32_e64 v5, v129, v5
	v_add_f32_e32 v4, v130, v4
	v_add_f32_e32 v5, v131, v5
	v_mfma_f32_32x32x16_bf16 v[64:79], v[96:99], v[36:39], v[64:79]
	v_add_f32_e64 v4, v132, v4
	v_add_f32_e64 v5, v133, v5
	v_add_f32_e64 v4, v134, v4
	v_add_f32_e64 v5, v135, v5
	v_add_f32_e64 v4, v136, v4
	v_add_f32_e64 v5, v137, v5
	v_mfma_f32_32x32x16_bf16 v[80:95], v[104:107], v[36:39], v[80:95]
	v_add_f32_e64 v4, v138, v4
	v_add_f32_e64 v5, v139, v5
	v_add_f32_e64 v4, v108, v4
	v_add_f32_e64 v5, v109, v5
	v_add_f32_e32 v4, v140, v4
	v_add_f32_e32 v5, v141, v5
	v_add_f32_e32 v4, v110, v4
	v_add_f32_e32 v5, v111, v5
	v_add_f32_e32 v2, v2, v4
	v_add_f32_e32 v3, v3, v5
	v_add_f32_e32 v192, v2, v3
	s_add_i32 s53, s53, 1
	s_add_i32 s14, s14, 4
	s_addk_i32 s76, 0x80
	s_add_i32 s10, s51, s53
	v_add_u32_e32 v251, 0xffffff80, v251
	s_cmp_ge_i32 s10, s26
	v_add_u32_e32 v190, 0x400, v190
	s_cbranch_scc1 .Lfox_exit_cp
	v_mov_b32_e32 v193, v192
	s_branch .LBB0_367
